# static per-XCD decode assignment keyed on blockIdx bit 7 (workgroups 0..127 stream the decode caches)
# baseline (speedup 1.0000x reference)
.LBB0_785:
	s_cmp_lt_i32 s96, 5
	s_cselect_b64 s[4:5], -1, 0
	s_cmp_gt_i32 s97, 4
	s_cselect_b64 s[6:7], -1, 0
	s_and_b64 s[4:5], s[4:5], s[6:7]
	s_andn2_b64 vcc, exec, s[4:5]
	s_cbranch_vccnz .LBB0_1063
	s_lshr_b32 s101, s2, 8
	s_lshl_b32 s101, s101, 7
	s_and_b32 s100, s2, 0x7f
	s_or_b32 s101, s101, s100
	s_bitcmp0_b32 s2, 7
	s_cselect_b32 s100, s101, 0x80
	s_and_b32 s10, s95, 0xffffffc0
	s_bfe_u32 s8, s95, 0x10006
	s_add_u32 s30, s38, 0x12300000
	s_addc_u32 s31, s39, 0
	s_mov_b32 s5, 0
	s_add_u32 s52, s38, 0x100000
	s_mul_i32 s4, s92, 0x60
	s_addc_u32 s53, s39, 0
	s_lshl_b64 s[4:5], s[4:5], 1
	s_add_u32 s56, s30, s4
	s_addc_u32 s57, s31, s5
	s_ashr_i32 s11, s10, 31
	s_lshr_b32 s5, s95, 7
	s_cmpk_lt_u32 s95, 0x80
	s_cselect_b64 s[58:59], -1, 0
	s_lshl_b32 s14, s5, 13
	s_mul_i32 s9, s92, 0x1200
	s_add_i32 s84, 0, 0x22000
	s_mul_i32 s12, s8, 0x1200
	s_add_i32 s83, 0, 0x22900
	s_lshr_b32 s13, s95, 4
	s_and_b32 s15, s14, 0x7fffc000
	s_lshl_b32 s78, s8, 5
	s_add_i32 s45, s84, s9
	s_lshl_b32 s3, s92, 5
	s_add_i32 s76, s83, s12
	s_add_i32 s77, s15, 0
	s_and_b32 s79, s13, 8
	s_or_b32 s80, s78, 8
	s_or_b32 s81, s78, 16
	s_or_b32 s82, s78, 24
	s_add_i32 s83, s83, s9
	s_add_i32 s84, s84, s12
	s_add_u32 s60, s38, 0x10f00000
	s_addc_u32 s61, s39, 0
	s_add_u32 s54, s38, 0x12000000
	s_addc_u32 s55, s39, 0
	s_lshl_b32 s9, s92, 8
	s_add_i32 s88, s9, 0
	v_mbcnt_hi_u32_b32 v187, -1, v254
	s_add_i32 s85, s77, 0x17400
	s_add_i32 s86, s14, 0
	s_add_i32 s87, s88, 0x24400
	s_add_i32 s88, s88, 0x16000
	s_and_b32 s12, 64, s95
	v_writelane_b32 v255, s90, 6
	v_and_b32_e32 v1, 64, v187
	s_cmp_eq_u32 s8, 0
	v_writelane_b32 v255, s91, 7
	s_mul_i32 s4, s92, 0x250
	v_xor_b32_e32 v0, 32, v187
	v_add_u32_e32 v188, 64, v1
	s_cselect_b64 s[8:9], -1, 0
	s_cmp_lg_u32 s12, 0
	v_cmp_lt_i32_e32 vcc, v0, v188
	v_writelane_b32 v255, s95, 8
	s_cselect_b64 s[62:63], -1, 0
	s_add_i32 s90, s4, 0
	s_mul_i32 s4, s92, 0x410
	v_add_u32_e32 v186, s10, v187
	v_cndmask_b32_e32 v0, v187, v0, vcc
	s_lshl_b32 s5, s5, 8
	v_writelane_b32 v255, s92, 5
	s_add_i32 s92, s4, 0
	s_add_i32 s93, 0, 0x21140
	v_lshlrev_b32_e32 v189, 2, v0
	v_cmp_eq_u32_e64 s[6:7], 0, v186
	s_add_i32 s89, s5, 0
	s_lshl_b64 s[64:65], s[10:11], 2
	s_add_i32 s91, s10, 0x200
	s_addk_i32 s92, 0x4c00
	v_mov_b32_e32 v121, 0
	s_mov_b32 s94, 0x8000
	s_movk_i32 s95, 0x600
	s_movk_i32 s96, 0x7fff
	s_movk_i32 s97, 0x50
	s_movk_i32 s50, 0x4000
	s_movk_i32 s51, 0x2000
	s_movk_i32 s4, 0x6000
	s_mov_b32 s5, 0xa000
	s_mov_b32 s48, 0xc000
	s_mov_b32 s49, 0xe000
	s_mov_b32 s74, 0x41000000
	s_lshl_b64 s[66:67], s[10:11], 1
	s_mov_b64 s[68:69], 0x19700400
	s_mov_b32 s75, 0x19700000
	v_mov_b32_e32 v123, s93
	v_mov_b32_e32 v138, 0xff800000
	s_branch .LBB0_789

.LBB0_1076:
	s_ashr_i32 s29, s28, 31
	s_lshl_b64 s[30:31], s[28:29], 19
	s_add_u32 s30, s3, s30
	s_addc_u32 s31, s45, s31
	s_and_b64 s[40:41], s[6:7], exec
	s_cselect_b32 s29, s31, s53
	s_cselect_b32 s65, s30, s52
	s_ashr_i32 s27, s26, 31
	s_lshl_b64 s[40:41], s[26:27], 19
	s_add_u32 s40, s62, s40
	s_addc_u32 s41, s63, s41
	s_and_b64 s[46:47], s[6:7], exec
	s_cselect_b32 s27, s41, s55
	s_cselect_b32 s66, s40, s54
	s_add_u32 s52, s52, 0x40080
	s_addc_u32 s53, s53, 0
	s_add_u32 s67, s54, 0x100
	v_mov_b32_e32 v0, 0
	s_addc_u32 s68, s55, 0
	s_mov_b32 s69, -2
	v_mov_b32_e32 v1, v0
	v_mov_b32_e32 v2, v0
	v_mov_b32_e32 v3, v0
	v_mov_b32_e32 v4, v0
	v_mov_b32_e32 v5, v0
	v_mov_b32_e32 v6, v0
	v_mov_b32_e32 v7, v0
	v_mov_b32_e32 v16, v0
	v_mov_b32_e32 v17, v0
	v_mov_b32_e32 v18, v0
	v_mov_b32_e32 v19, v0
	v_mov_b32_e32 v20, v0
	v_mov_b32_e32 v21, v0
	v_mov_b32_e32 v22, v0
	v_mov_b32_e32 v23, v0
	v_mov_b32_e32 v32, v0
	v_mov_b32_e32 v33, v0
	v_mov_b32_e32 v34, v0
	v_mov_b32_e32 v35, v0
	v_mov_b32_e32 v36, v0
	v_mov_b32_e32 v37, v0
	v_mov_b32_e32 v38, v0
	v_mov_b32_e32 v39, v0
	v_mov_b32_e32 v48, v0
	v_mov_b32_e32 v49, v0
	v_mov_b32_e32 v50, v0
	v_mov_b32_e32 v51, v0
	v_mov_b32_e32 v52, v0
	v_mov_b32_e32 v53, v0
	v_mov_b32_e32 v54, v0
	v_mov_b32_e32 v55, v0
	v_mov_b32_e32 v8, v0
	v_mov_b32_e32 v9, v0
	v_mov_b32_e32 v10, v0
	v_mov_b32_e32 v11, v0
	v_mov_b32_e32 v12, v0
	v_mov_b32_e32 v13, v0
	v_mov_b32_e32 v14, v0
	v_mov_b32_e32 v15, v0
	v_mov_b32_e32 v24, v0
	v_mov_b32_e32 v25, v0
	v_mov_b32_e32 v26, v0
	v_mov_b32_e32 v27, v0
	v_mov_b32_e32 v28, v0
	v_mov_b32_e32 v29, v0
	v_mov_b32_e32 v30, v0
	v_mov_b32_e32 v31, v0
	v_mov_b32_e32 v40, v0
	v_mov_b32_e32 v41, v0
	v_mov_b32_e32 v42, v0
	v_mov_b32_e32 v43, v0
	v_mov_b32_e32 v44, v0
	v_mov_b32_e32 v45, v0
	v_mov_b32_e32 v46, v0
	v_mov_b32_e32 v47, v0
	v_mov_b32_e32 v56, v0
	v_mov_b32_e32 v57, v0
	v_mov_b32_e32 v58, v0
	v_mov_b32_e32 v59, v0
	v_mov_b32_e32 v60, v0
	v_mov_b32_e32 v61, v0
	v_mov_b32_e32 v62, v0
	v_mov_b32_e32 v63, v0
	v_mov_b32_e32 v64, v0
	v_mov_b32_e32 v65, v0
	v_mov_b32_e32 v66, v0
	v_mov_b32_e32 v67, v0
	v_mov_b32_e32 v68, v0
	v_mov_b32_e32 v69, v0
	v_mov_b32_e32 v70, v0
	v_mov_b32_e32 v71, v0
	v_mov_b32_e32 v80, v0
	v_mov_b32_e32 v81, v0
	v_mov_b32_e32 v82, v0
	v_mov_b32_e32 v83, v0
	v_mov_b32_e32 v84, v0
	v_mov_b32_e32 v85, v0
	v_mov_b32_e32 v86, v0
	v_mov_b32_e32 v87, v0
	v_mov_b32_e32 v96, v0
	v_mov_b32_e32 v97, v0
	v_mov_b32_e32 v98, v0
	v_mov_b32_e32 v99, v0
	v_mov_b32_e32 v100, v0
	v_mov_b32_e32 v101, v0
	v_mov_b32_e32 v102, v0
	v_mov_b32_e32 v103, v0
	v_mov_b32_e32 v112, v0
	v_mov_b32_e32 v113, v0
	v_mov_b32_e32 v114, v0
	v_mov_b32_e32 v115, v0
	v_mov_b32_e32 v116, v0
	v_mov_b32_e32 v117, v0
	v_mov_b32_e32 v118, v0
	v_mov_b32_e32 v119, v0
	v_mov_b32_e32 v72, v0
	v_mov_b32_e32 v73, v0
	v_mov_b32_e32 v74, v0
	v_mov_b32_e32 v75, v0
	v_mov_b32_e32 v76, v0
	v_mov_b32_e32 v77, v0
	v_mov_b32_e32 v78, v0
	v_mov_b32_e32 v79, v0
	v_mov_b32_e32 v88, v0
	v_mov_b32_e32 v89, v0
	v_mov_b32_e32 v90, v0
	v_mov_b32_e32 v91, v0
	v_mov_b32_e32 v92, v0
	v_mov_b32_e32 v93, v0
	v_mov_b32_e32 v94, v0
	v_mov_b32_e32 v95, v0
	v_mov_b32_e32 v104, v0
	v_mov_b32_e32 v105, v0
	v_mov_b32_e32 v106, v0
	v_mov_b32_e32 v107, v0
	v_mov_b32_e32 v108, v0
	v_mov_b32_e32 v109, v0
	v_mov_b32_e32 v110, v0
	v_mov_b32_e32 v111, v0
	v_mov_b32_e32 v120, v0
	v_mov_b32_e32 v121, v0
	v_mov_b32_e32 v122, v0
	v_mov_b32_e32 v123, v0
	v_mov_b32_e32 v124, v0
	v_mov_b32_e32 v125, v0
	v_mov_b32_e32 v126, v0
	v_mov_b32_e32 v127, v0
	s_nop 0
.LBB0_1077:
	ds_read_b128 v[144:147], v154
	ds_read_b128 v[158:161], v154 offset:1024
	ds_read_b128 v[162:165], v154 offset:2048
	ds_read_b128 v[166:169], v154 offset:3072
	ds_read_b128 v[170:173], v155
	ds_read_b128 v[174:177], v155 offset:1024
	ds_read_b128 v[178:181], v155 offset:2048
	ds_read_b128 v[182:185], v155 offset:3072
	s_add_u32 s46, s52, 0xfffc0080
	s_addc_u32 s47, s53, -1
	s_cmp_eq_u32 s69, 12
	s_cselect_b32 s57, s29, s47
	s_cselect_b32 s56, s65, s46
	s_cselect_b32 s55, s27, s68
	s_cselect_b32 s54, s66, s67
	v_lshl_add_u64 v[148:149], s[52:53], 0, v[136:137]
	s_add_i32 m0, s43, 0xc000
	ds_read_b128 v[186:189], v156
	ds_read_b128 v[190:193], v156 offset:1024
	ds_read_b128 v[198:201], v156 offset:2048
	ds_read_b128 v[202:205], v156 offset:3072
	ds_read_b128 v[206:209], v156 offset:4096
	ds_read_b128 v[210:213], v156 offset:5120
	ds_read_b128 v[214:217], v156 offset:6144
	ds_read_b128 v[218:221], v156 offset:7168
	global_load_lds_dwordx4 v[148:149], off
	v_lshl_add_u64 v[148:149], s[52:53], 0, v[138:139]
	s_add_i32 m0, s43, 0xe000
	s_nop 0
	global_load_lds_dwordx4 v[148:149], off
	s_waitcnt vmcnt(8)
	s_waitcnt lgkmcnt(0)
	s_barrier
	s_setprio 1
	s_waitcnt lgkmcnt(0)
	v_mfma_f32_16x16x32_bf16 v[124:127], v[144:147], v[186:189], v[124:127]
	v_mfma_f32_16x16x32_bf16 v[120:123], v[162:165], v[186:189], v[120:123]
	v_mfma_f32_16x16x32_bf16 v[108:111], v[144:147], v[198:201], v[108:111]
	v_mfma_f32_16x16x32_bf16 v[104:107], v[162:165], v[198:201], v[104:107]
	v_mfma_f32_16x16x32_bf16 v[92:95], v[144:147], v[206:209], v[92:95]
	v_mfma_f32_16x16x32_bf16 v[88:91], v[162:165], v[206:209], v[88:91]
	v_mfma_f32_16x16x32_bf16 v[76:79], v[144:147], v[214:217], v[76:79]
	v_mfma_f32_16x16x32_bf16 v[72:75], v[162:165], v[214:217], v[72:75]
	v_mfma_f32_16x16x32_bf16 v[124:127], v[158:161], v[190:193], v[124:127]
	v_mfma_f32_16x16x32_bf16 v[120:123], v[166:169], v[190:193], v[120:123]
	v_mfma_f32_16x16x32_bf16 v[108:111], v[158:161], v[202:205], v[108:111]
	v_mfma_f32_16x16x32_bf16 v[104:107], v[166:169], v[202:205], v[104:107]
	v_mfma_f32_16x16x32_bf16 v[92:95], v[158:161], v[210:213], v[92:95]
	v_mfma_f32_16x16x32_bf16 v[88:91], v[166:169], v[210:213], v[88:91]
	v_mfma_f32_16x16x32_bf16 v[76:79], v[158:161], v[218:221], v[76:79]
	v_mfma_f32_16x16x32_bf16 v[72:75], v[166:169], v[218:221], v[72:75]
	s_setprio 0
	s_setprio 1
	v_mfma_f32_16x16x32_bf16 v[116:119], v[170:173], v[186:189], v[116:119]
	v_mfma_f32_16x16x32_bf16 v[112:115], v[178:181], v[186:189], v[112:115]
	v_mfma_f32_16x16x32_bf16 v[100:103], v[170:173], v[198:201], v[100:103]
	v_mfma_f32_16x16x32_bf16 v[96:99], v[178:181], v[198:201], v[96:99]
	v_mfma_f32_16x16x32_bf16 v[84:87], v[170:173], v[206:209], v[84:87]
	v_mfma_f32_16x16x32_bf16 v[80:83], v[178:181], v[206:209], v[80:83]
	v_mfma_f32_16x16x32_bf16 v[68:71], v[170:173], v[214:217], v[68:71]
	v_mfma_f32_16x16x32_bf16 v[64:67], v[178:181], v[214:217], v[64:67]
	v_mfma_f32_16x16x32_bf16 v[116:119], v[174:177], v[190:193], v[116:119]
	v_mfma_f32_16x16x32_bf16 v[112:115], v[182:185], v[190:193], v[112:115]
	v_mfma_f32_16x16x32_bf16 v[100:103], v[174:177], v[202:205], v[100:103]
	v_mfma_f32_16x16x32_bf16 v[96:99], v[182:185], v[202:205], v[96:99]
	v_mfma_f32_16x16x32_bf16 v[84:87], v[174:177], v[210:213], v[84:87]
	v_mfma_f32_16x16x32_bf16 v[80:83], v[182:185], v[210:213], v[80:83]
	v_mfma_f32_16x16x32_bf16 v[68:71], v[174:177], v[218:221], v[68:71]
	v_mfma_f32_16x16x32_bf16 v[64:67], v[182:185], v[218:221], v[64:67]
	s_setprio 0
	s_barrier
	s_add_i32 s46, s61, s4
	v_lshl_add_u64 v[148:149], s[54:55], 0, v[132:133]
	s_mov_b32 m0, s46
	ds_read_b128 v[186:189], v156 offset:16384
	ds_read_b128 v[190:193], v156 offset:17408
	ds_read_b128 v[198:201], v156 offset:18432
	ds_read_b128 v[202:205], v156 offset:19456
	ds_read_b128 v[206:209], v156 offset:20480
	ds_read_b128 v[210:213], v156 offset:21504
	ds_read_b128 v[214:217], v156 offset:22528
	ds_read_b128 v[218:221], v156 offset:23552
	global_load_lds_dwordx4 v[148:149], off
	s_add_i32 m0, s46, 0x2000
	s_add_u32 s46, s54, 0x40000
	v_lshl_add_u64 v[194:195], s[54:55], 0, v[128:129]
	s_addc_u32 s47, s55, 0
	s_add_i32 s70, s64, s4
	global_load_lds_dwordx4 v[194:195], off
	v_lshl_add_u64 v[196:197], s[46:47], 0, v[132:133]
	s_mov_b32 m0, s70
	v_lshl_add_u64 v[222:223], s[56:57], 0, v[130:131]
	global_load_lds_dwordx4 v[196:197], off
	v_lshl_add_u64 v[196:197], s[46:47], 0, v[128:129]
	s_add_i32 m0, s70, 0x2000
	s_nop 0
	global_load_lds_dwordx4 v[196:197], off
	v_lshl_add_u64 v[196:197], s[56:57], 0, v[134:135]
	s_mov_b32 m0, s43
	s_nop 0
	global_load_lds_dwordx4 v[196:197], off
	s_mov_b32 m0, s48
	s_nop 0
	global_load_lds_dwordx4 v[222:223], off
	s_nop 0
	s_waitcnt vmcnt(8)
	s_waitcnt lgkmcnt(0)
	s_barrier
	s_setprio 1
	s_waitcnt lgkmcnt(0)
	v_mfma_f32_16x16x32_bf16 v[60:63], v[144:147], v[186:189], v[60:63]
	v_mfma_f32_16x16x32_bf16 v[56:59], v[162:165], v[186:189], v[56:59]
	v_mfma_f32_16x16x32_bf16 v[44:47], v[144:147], v[198:201], v[44:47]
	v_mfma_f32_16x16x32_bf16 v[40:43], v[162:165], v[198:201], v[40:43]
	v_mfma_f32_16x16x32_bf16 v[28:31], v[144:147], v[206:209], v[28:31]
	v_mfma_f32_16x16x32_bf16 v[24:27], v[162:165], v[206:209], v[24:27]
	v_mfma_f32_16x16x32_bf16 v[12:15], v[144:147], v[214:217], v[12:15]
	v_mfma_f32_16x16x32_bf16 v[8:11], v[162:165], v[214:217], v[8:11]
	v_mfma_f32_16x16x32_bf16 v[60:63], v[158:161], v[190:193], v[60:63]
	v_mfma_f32_16x16x32_bf16 v[56:59], v[166:169], v[190:193], v[56:59]
	v_mfma_f32_16x16x32_bf16 v[44:47], v[158:161], v[202:205], v[44:47]
	v_mfma_f32_16x16x32_bf16 v[40:43], v[166:169], v[202:205], v[40:43]
	v_mfma_f32_16x16x32_bf16 v[28:31], v[158:161], v[210:213], v[28:31]
	v_mfma_f32_16x16x32_bf16 v[24:27], v[166:169], v[210:213], v[24:27]
	v_mfma_f32_16x16x32_bf16 v[12:15], v[158:161], v[218:221], v[12:15]
	v_mfma_f32_16x16x32_bf16 v[8:11], v[166:169], v[218:221], v[8:11]
	s_setprio 0
	s_setprio 1
	v_mfma_f32_16x16x32_bf16 v[52:55], v[170:173], v[186:189], v[52:55]
	v_mfma_f32_16x16x32_bf16 v[48:51], v[178:181], v[186:189], v[48:51]
	v_mfma_f32_16x16x32_bf16 v[36:39], v[170:173], v[198:201], v[36:39]
	v_mfma_f32_16x16x32_bf16 v[32:35], v[178:181], v[198:201], v[32:35]
	v_mfma_f32_16x16x32_bf16 v[20:23], v[170:173], v[206:209], v[20:23]
	v_mfma_f32_16x16x32_bf16 v[16:19], v[178:181], v[206:209], v[16:19]
	v_mfma_f32_16x16x32_bf16 v[4:7], v[170:173], v[214:217], v[4:7]
	v_mfma_f32_16x16x32_bf16 v[0:3], v[178:181], v[214:217], v[0:3]
	v_mfma_f32_16x16x32_bf16 v[52:55], v[174:177], v[190:193], v[52:55]
	v_mfma_f32_16x16x32_bf16 v[48:51], v[182:185], v[190:193], v[48:51]
	v_mfma_f32_16x16x32_bf16 v[36:39], v[174:177], v[202:205], v[36:39]
	v_mfma_f32_16x16x32_bf16 v[32:35], v[182:185], v[202:205], v[32:35]
	v_mfma_f32_16x16x32_bf16 v[20:23], v[174:177], v[210:213], v[20:23]
	v_mfma_f32_16x16x32_bf16 v[16:19], v[182:185], v[210:213], v[16:19]
	v_mfma_f32_16x16x32_bf16 v[4:7], v[174:177], v[218:221], v[4:7]
	v_mfma_f32_16x16x32_bf16 v[0:3], v[182:185], v[218:221], v[0:3]
	s_setprio 0
	s_barrier
	s_add_i32 s70, 0, 0x18000
	v_add_u32_e32 v157, s70, v152
	s_add_i32 s71, 0, 0x1c000
	ds_read_b128 v[144:147], v157
	ds_read_b128 v[158:161], v157 offset:1024
	ds_read_b128 v[162:165], v157 offset:2048
	ds_read_b128 v[166:169], v157 offset:3072
	v_add_u32_e32 v157, s71, v152
	ds_read_b128 v[170:173], v157
	ds_read_b128 v[174:177], v157 offset:1024
	ds_read_b128 v[178:181], v157 offset:2048
	ds_read_b128 v[182:185], v157 offset:3072
	s_add_u32 s46, s56, 0x40000
	s_addc_u32 s47, s57, 0
	s_mov_b32 m0, s49
	v_lshl_add_u64 v[224:225], s[46:47], 0, v[134:135]
	ds_read_b128 v[186:189], v156 offset:32768
	ds_read_b128 v[190:193], v156 offset:33792
	ds_read_b128 v[198:201], v156 offset:34816
	ds_read_b128 v[202:205], v156 offset:35840
	ds_read_b128 v[206:209], v156 offset:36864
	ds_read_b128 v[210:213], v156 offset:37888
	ds_read_b128 v[214:217], v156 offset:38912
	ds_read_b128 v[218:221], v156 offset:39936
	global_load_lds_dwordx4 v[224:225], off
	v_lshl_add_u64 v[224:225], s[46:47], 0, v[130:131]
	s_mov_b32 m0, s50
	s_nop 0
	global_load_lds_dwordx4 v[224:225], off
	s_nop 0
	s_waitcnt vmcnt(8)
	s_waitcnt lgkmcnt(0)
	s_barrier
	s_setprio 1
	s_waitcnt lgkmcnt(0)
	v_mfma_f32_16x16x32_bf16 v[124:127], v[144:147], v[186:189], v[124:127]
	v_mfma_f32_16x16x32_bf16 v[120:123], v[162:165], v[186:189], v[120:123]
	v_mfma_f32_16x16x32_bf16 v[108:111], v[144:147], v[198:201], v[108:111]
	v_mfma_f32_16x16x32_bf16 v[104:107], v[162:165], v[198:201], v[104:107]
	v_mfma_f32_16x16x32_bf16 v[92:95], v[144:147], v[206:209], v[92:95]
	v_mfma_f32_16x16x32_bf16 v[88:91], v[162:165], v[206:209], v[88:91]
	v_mfma_f32_16x16x32_bf16 v[76:79], v[144:147], v[214:217], v[76:79]
	v_mfma_f32_16x16x32_bf16 v[72:75], v[162:165], v[214:217], v[72:75]
	v_mfma_f32_16x16x32_bf16 v[124:127], v[158:161], v[190:193], v[124:127]
	v_mfma_f32_16x16x32_bf16 v[120:123], v[166:169], v[190:193], v[120:123]
	v_mfma_f32_16x16x32_bf16 v[108:111], v[158:161], v[202:205], v[108:111]
	v_mfma_f32_16x16x32_bf16 v[104:107], v[166:169], v[202:205], v[104:107]
	v_mfma_f32_16x16x32_bf16 v[92:95], v[158:161], v[210:213], v[92:95]
	v_mfma_f32_16x16x32_bf16 v[88:91], v[166:169], v[210:213], v[88:91]
	v_mfma_f32_16x16x32_bf16 v[76:79], v[158:161], v[218:221], v[76:79]
	v_mfma_f32_16x16x32_bf16 v[72:75], v[166:169], v[218:221], v[72:75]
	s_setprio 0
	s_setprio 1
	v_mfma_f32_16x16x32_bf16 v[116:119], v[170:173], v[186:189], v[116:119]
	v_mfma_f32_16x16x32_bf16 v[112:115], v[178:181], v[186:189], v[112:115]
	v_mfma_f32_16x16x32_bf16 v[100:103], v[170:173], v[198:201], v[100:103]
	v_mfma_f32_16x16x32_bf16 v[96:99], v[178:181], v[198:201], v[96:99]
	v_mfma_f32_16x16x32_bf16 v[84:87], v[170:173], v[206:209], v[84:87]
	v_mfma_f32_16x16x32_bf16 v[80:83], v[178:181], v[206:209], v[80:83]
	v_mfma_f32_16x16x32_bf16 v[68:71], v[170:173], v[214:217], v[68:71]
	v_mfma_f32_16x16x32_bf16 v[64:67], v[178:181], v[214:217], v[64:67]
	v_mfma_f32_16x16x32_bf16 v[116:119], v[174:177], v[190:193], v[116:119]
	v_mfma_f32_16x16x32_bf16 v[112:115], v[182:185], v[190:193], v[112:115]
	v_mfma_f32_16x16x32_bf16 v[100:103], v[174:177], v[202:205], v[100:103]
	v_mfma_f32_16x16x32_bf16 v[96:99], v[182:185], v[202:205], v[96:99]
	v_mfma_f32_16x16x32_bf16 v[84:87], v[174:177], v[210:213], v[84:87]
	v_mfma_f32_16x16x32_bf16 v[80:83], v[182:185], v[210:213], v[80:83]
	v_mfma_f32_16x16x32_bf16 v[68:71], v[174:177], v[218:221], v[68:71]
	v_mfma_f32_16x16x32_bf16 v[64:67], v[182:185], v[218:221], v[64:67]
	s_setprio 0
	s_barrier
	s_add_i32 s46, s70, s4
	v_lshl_add_u64 v[148:149], v[148:149], 0, s[16:17]
	s_mov_b32 m0, s46
	ds_read_b128 v[186:189], v156 offset:49152
	ds_read_b128 v[190:193], v156 offset:50176
	ds_read_b128 v[198:201], v156 offset:51200
	ds_read_b128 v[202:205], v156 offset:52224
	ds_read_b128 v[206:209], v156 offset:53248
	ds_read_b128 v[210:213], v156 offset:54272
	ds_read_b128 v[214:217], v156 offset:55296
	ds_read_b128 v[218:221], v156 offset:56320
	global_load_lds_dwordx4 v[148:149], off
	s_add_i32 m0, s46, 0x2000
	s_add_u32 s46, s54, 0x40080
	v_lshl_add_u64 v[148:149], v[194:195], 0, s[16:17]
	s_addc_u32 s47, s55, 0
	s_add_i32 s54, s71, s4
	global_load_lds_dwordx4 v[148:149], off
	v_lshl_add_u64 v[148:149], s[46:47], 0, v[132:133]
	s_mov_b32 m0, s54
	s_nop 0
	global_load_lds_dwordx4 v[148:149], off
	v_lshl_add_u64 v[148:149], s[46:47], 0, v[128:129]
	s_add_i32 m0, s54, 0x2000
	s_nop 0
	global_load_lds_dwordx4 v[148:149], off
	v_lshl_add_u64 v[148:149], v[196:197], 0, s[16:17]
	s_mov_b32 m0, s58
	s_nop 0
	global_load_lds_dwordx4 v[148:149], off
	v_lshl_add_u64 v[148:149], v[222:223], 0, s[16:17]
	s_mov_b32 m0, s59
	s_nop 0
	global_load_lds_dwordx4 v[148:149], off
	s_waitcnt vmcnt(8)
	s_waitcnt lgkmcnt(0)
	s_barrier
	s_setprio 1
	s_waitcnt lgkmcnt(0)
	v_mfma_f32_16x16x32_bf16 v[60:63], v[144:147], v[186:189], v[60:63]
	v_mfma_f32_16x16x32_bf16 v[56:59], v[162:165], v[186:189], v[56:59]
	v_mfma_f32_16x16x32_bf16 v[44:47], v[144:147], v[198:201], v[44:47]
	v_mfma_f32_16x16x32_bf16 v[40:43], v[162:165], v[198:201], v[40:43]
	v_mfma_f32_16x16x32_bf16 v[28:31], v[144:147], v[206:209], v[28:31]
	v_mfma_f32_16x16x32_bf16 v[24:27], v[162:165], v[206:209], v[24:27]
	v_mfma_f32_16x16x32_bf16 v[12:15], v[144:147], v[214:217], v[12:15]
	v_mfma_f32_16x16x32_bf16 v[8:11], v[162:165], v[214:217], v[8:11]
	v_mfma_f32_16x16x32_bf16 v[60:63], v[158:161], v[190:193], v[60:63]
	v_mfma_f32_16x16x32_bf16 v[56:59], v[166:169], v[190:193], v[56:59]
	v_mfma_f32_16x16x32_bf16 v[44:47], v[158:161], v[202:205], v[44:47]
	v_mfma_f32_16x16x32_bf16 v[40:43], v[166:169], v[202:205], v[40:43]
	v_mfma_f32_16x16x32_bf16 v[28:31], v[158:161], v[210:213], v[28:31]
	v_mfma_f32_16x16x32_bf16 v[24:27], v[166:169], v[210:213], v[24:27]
	v_mfma_f32_16x16x32_bf16 v[12:15], v[158:161], v[218:221], v[12:15]
	v_mfma_f32_16x16x32_bf16 v[8:11], v[166:169], v[218:221], v[8:11]
	s_setprio 0
	s_setprio 1
	v_mfma_f32_16x16x32_bf16 v[52:55], v[170:173], v[186:189], v[52:55]
	v_mfma_f32_16x16x32_bf16 v[48:51], v[178:181], v[186:189], v[48:51]
	v_mfma_f32_16x16x32_bf16 v[36:39], v[170:173], v[198:201], v[36:39]
	v_mfma_f32_16x16x32_bf16 v[32:35], v[178:181], v[198:201], v[32:35]
	v_mfma_f32_16x16x32_bf16 v[20:23], v[170:173], v[206:209], v[20:23]
	v_mfma_f32_16x16x32_bf16 v[16:19], v[178:181], v[206:209], v[16:19]
	v_mfma_f32_16x16x32_bf16 v[4:7], v[170:173], v[214:217], v[4:7]
	v_mfma_f32_16x16x32_bf16 v[0:3], v[178:181], v[214:217], v[0:3]
	v_mfma_f32_16x16x32_bf16 v[52:55], v[174:177], v[190:193], v[52:55]
	v_mfma_f32_16x16x32_bf16 v[48:51], v[182:185], v[190:193], v[48:51]
	v_mfma_f32_16x16x32_bf16 v[36:39], v[174:177], v[202:205], v[36:39]
	v_mfma_f32_16x16x32_bf16 v[32:35], v[182:185], v[202:205], v[32:35]
	v_mfma_f32_16x16x32_bf16 v[20:23], v[174:177], v[210:213], v[20:23]
	v_mfma_f32_16x16x32_bf16 v[16:19], v[182:185], v[210:213], v[16:19]
	v_mfma_f32_16x16x32_bf16 v[4:7], v[174:177], v[218:221], v[4:7]
	v_mfma_f32_16x16x32_bf16 v[0:3], v[182:185], v[218:221], v[0:3]
	s_setprio 0
	s_barrier
	s_add_i32 s69, s69, 2
	s_add_u32 s52, s52, 0x100
	s_addc_u32 s53, s53, 0
	s_add_u32 s67, s67, 0x100
	s_addc_u32 s68, s68, 0
	s_cmp_gt_u32 s69, 13
	s_cbranch_scc0 .LBB0_1077
	s_and_b64 vcc, exec, s[18:19]
	s_cbranch_vccz .LBB0_1080
	s_barrier
